# speedup vs baseline: 1.0185x; 1.0142x over previous
.Lxl_exit_1:
	buffer_inv sc0
	s_branch .LBB0_370
